# SwiGLU epilogue arithmetic: row scale folded into the sigmoid argument and the reciprocal, 8-wide batches (no hazard pads), 8 packed multiplies instead of 16
# speedup vs baseline: 1.0157x; 1.0029x over previous
; __device__ __forceinline__ u32x4 pack8(const f32x4 a, const f32x4 b) { u32x4 w; w.x = cvt_pk_bf16(a[0], a[1]); w.y = cvt_pk_bf16(a[2], a[3]); w.z = cvt_pk_bf16(b[0], b[1]); w.w = cvt_pk_bf16(b[2], b[3]); return w; }
; __device__ __forceinline__ float rstd_of(const float* ssq, int row) { const f32x4 a = *(const f32x4*)(ssq + (size_t)row * 4);
;     return __builtin_amdgcn_rsqf(((a[0] + a[1]) + (a[2] + a[3])) * (1.0f / 1024.0f) + 1e-6f); }
; __device__ __forceinline__ float sigm(float g) { return __builtin_amdgcn_rcpf(1.0f + __builtin_amdgcn_exp2f(-1.4426950408889634f * g)); }
;     __device__ __forceinline__ void operator()(const f32x4 (&acc)[2][2][4][2], const Unit& u, int wr, int wc, int fr, int fq) const {
;     ...
;             for (int m = 0; m < 4; ++m) { if (m == 0) asm volatile("" ::: "memory"); const int row = row0 + ai * HALF + m * 16; const float rs = rstd_of(ssq, row);
;                 f32x4 o[2];
; #pragma unroll
;                 for (int n = 0; n < 2; ++n) { const f32x4 g = acc[ai][0][m][n] * rs, up = acc[ai][1][m][n] * rs;
; #pragma unroll
;                     for (int e = 0; e < 4; ++e) o[n][e] = g[e] * sigm(g[e]) * up[e]; }
;                 *(u32x4*)(O + (size_t)row * 2816 + col0) = pack8(o[0], o[1]); }
.LBB0_121:
	v_lshl_add_u32 v136, s0, 8, v140
	v_ashrrev_i32_e32 v137, 31, v136
	v_lshl_add_u64 v[144:145], v[136:137], 4, s[18:19]
	global_load_dwordx4 v[150:153], v[144:145], off
	global_load_dwordx4 v[154:157], v[144:145], off offset:256
	global_load_dwordx4 v[158:161], v[144:145], off offset:512
	global_load_dwordx4 v[162:165], v[144:145], off offset:768
	global_load_dwordx4 v[166:169], v[144:145], off offset:2048
	global_load_dwordx4 v[170:173], v[144:145], off offset:2304
	global_load_dwordx4 v[174:177], v[144:145], off offset:2560
	global_load_dwordx4 v[178:181], v[144:145], off offset:2816
	v_lshl_or_b32 v138, s1, 7, v142
	v_ashrrev_i32_e32 v139, 31, v138
	s_andn2_b64 vcc, exec, s[6:7]
	s_waitcnt vmcnt(7)
	v_mov_b64_e32 v[144:145], v[150:151]
	v_mov_b64_e32 v[146:147], v[152:153]
	v_mov_b32_e32 v148, v145
	v_mov_b32_e32 v149, v146
	v_mov_b32_e32 v145, v147
	v_pk_add_f32 v[144:145], v[148:149], v[144:145]
	s_nop 0
	v_add_f32_e32 v137, v144, v145
	v_fmamk_f32 v137, v137, 0x3a800000, v231
	v_rsq_f32_e32 v144, v137
	v_mov_b32_e32 v191, v137
	v_mul_f32_e32 v190, 0xbfb8aa3b, v144
	v_mul_f32_e32 v182, v126, v190
	v_mul_f32_e32 v183, v127, v190
	v_mul_f32_e32 v184, v128, v190
	v_mul_f32_e32 v185, v129, v190
	v_mul_f32_e32 v186, v122, v190
	v_mul_f32_e32 v187, v123, v190
	v_mul_f32_e32 v188, v124, v190
	v_mul_f32_e32 v189, v125, v190
	v_exp_f32_e32 v182, v182
	v_exp_f32_e32 v183, v183
	v_exp_f32_e32 v184, v184
	v_exp_f32_e32 v185, v185
	v_exp_f32_e32 v186, v186
	v_exp_f32_e32 v187, v187
	v_exp_f32_e32 v188, v188
	v_exp_f32_e32 v189, v189
	v_fma_f32 v182, v182, v191, v191
	v_fma_f32 v183, v183, v191, v191
	v_fma_f32 v184, v184, v191, v191
	v_fma_f32 v185, v185, v191, v191
	v_fma_f32 v186, v186, v191, v191
	v_fma_f32 v187, v187, v191, v191
	v_fma_f32 v188, v188, v191, v191
	v_fma_f32 v189, v189, v191, v191
	v_rcp_f32_e32 v182, v182
	v_rcp_f32_e32 v183, v183
	v_rcp_f32_e32 v184, v184
	v_rcp_f32_e32 v185, v185
	v_rcp_f32_e32 v186, v186
	v_rcp_f32_e32 v187, v187
	v_rcp_f32_e32 v188, v188
	v_rcp_f32_e32 v189, v189
	v_pk_mul_f32 v[118:119], v[126:127], v[118:119]
	v_pk_mul_f32 v[120:121], v[128:129], v[120:121]
	v_pk_mul_f32 v[122:123], v[122:123], v[114:115]
	v_pk_mul_f32 v[124:125], v[124:125], v[116:117]
	v_pk_mul_f32 v[118:119], v[118:119], v[182:183]
	v_pk_mul_f32 v[120:121], v[120:121], v[184:185]
	v_pk_mul_f32 v[122:123], v[122:123], v[186:187]
	v_pk_mul_f32 v[124:125], v[124:125], v[188:189]
	v_cvt_pk_bf16_f32 v114, v118, v119
	v_mov_b64_e32 v[118:119], s[16:17]
	v_cvt_pk_bf16_f32 v115, v120, v121
	v_cvt_pk_bf16_f32 v116, v122, v123
	v_mad_i64_i32 v[122:123], s[0:1], v136, s92, v[118:119]
	v_lshlrev_b64 v[120:121], 1, v[138:139]
	v_cvt_pk_bf16_f32 v117, v124, v125
	v_lshl_add_u64 v[122:123], v[122:123], 0, v[120:121]
	global_store_dwordx4 v[122:123], v[114:117], off
	s_nop 1
	v_or_b32_e32 v114, 16, v136
	v_ashrrev_i32_e32 v115, 31, v114
	v_lshl_add_u64 v[116:117], v[114:115], 4, s[18:19]
	s_waitcnt vmcnt(7)
	v_mov_b64_e32 v[122:123], v[154:155]
	v_mov_b64_e32 v[124:125], v[156:157]
	v_mov_b32_e32 v116, v123
	v_mov_b32_e32 v117, v124
	v_mov_b32_e32 v123, v125
	v_pk_add_f32 v[116:117], v[116:117], v[122:123]
	s_nop 0
	v_add_f32_e32 v115, v116, v117
	v_fmamk_f32 v115, v115, 0x3a800000, v231
	v_rsq_f32_e32 v116, v115
	v_mov_b32_e32 v191, v115
	v_mul_f32_e32 v190, 0xbfb8aa3b, v116
	v_mul_f32_e32 v182, v108, v190
	v_mul_f32_e32 v183, v109, v190
	v_mul_f32_e32 v184, v110, v190
	v_mul_f32_e32 v185, v111, v190
	v_mul_f32_e32 v186, v104, v190
	v_mul_f32_e32 v187, v105, v190
	v_mul_f32_e32 v188, v106, v190
	v_mul_f32_e32 v189, v107, v190
	v_exp_f32_e32 v182, v182
	v_exp_f32_e32 v183, v183
	v_exp_f32_e32 v184, v184
	v_exp_f32_e32 v185, v185
	v_exp_f32_e32 v186, v186
	v_exp_f32_e32 v187, v187
	v_exp_f32_e32 v188, v188
	v_exp_f32_e32 v189, v189
	v_fma_f32 v182, v182, v191, v191
	v_fma_f32 v183, v183, v191, v191
	v_fma_f32 v184, v184, v191, v191
	v_fma_f32 v185, v185, v191, v191
	v_fma_f32 v186, v186, v191, v191
	v_fma_f32 v187, v187, v191, v191
	v_fma_f32 v188, v188, v191, v191
	v_fma_f32 v189, v189, v191, v191
	v_rcp_f32_e32 v182, v182
	v_rcp_f32_e32 v183, v183
	v_rcp_f32_e32 v184, v184
	v_rcp_f32_e32 v185, v185
	v_rcp_f32_e32 v186, v186
	v_rcp_f32_e32 v187, v187
	v_rcp_f32_e32 v188, v188
	v_rcp_f32_e32 v189, v189
	v_pk_mul_f32 v[100:101], v[108:109], v[100:101]
	v_pk_mul_f32 v[102:103], v[110:111], v[102:103]
	v_pk_mul_f32 v[104:105], v[104:105], v[96:97]
	v_pk_mul_f32 v[106:107], v[106:107], v[98:99]
	v_pk_mul_f32 v[100:101], v[100:101], v[182:183]
	v_pk_mul_f32 v[102:103], v[102:103], v[184:185]
	v_pk_mul_f32 v[104:105], v[104:105], v[186:187]
	v_pk_mul_f32 v[106:107], v[106:107], v[188:189]
	v_cvt_pk_bf16_f32 v96, v100, v101
	v_mad_i64_i32 v[100:101], s[0:1], v114, s92, v[118:119]
	v_cvt_pk_bf16_f32 v97, v102, v103
	v_cvt_pk_bf16_f32 v98, v104, v105
	v_cvt_pk_bf16_f32 v99, v106, v107
	v_lshl_add_u64 v[100:101], v[100:101], 0, v[120:121]
	global_store_dwordx4 v[100:101], v[96:99], off
	s_nop 1
	v_or_b32_e32 v96, 32, v136
	v_ashrrev_i32_e32 v97, 31, v96
	v_lshl_add_u64 v[98:99], v[96:97], 4, s[18:19]
	s_waitcnt vmcnt(7)
; __device__ __forceinline__ u32x4 pack8(const f32x4 a, const f32x4 b) { u32x4 w; w.x = cvt_pk_bf16(a[0], a[1]); w.y = cvt_pk_bf16(a[2], a[3]); w.z = cvt_pk_bf16(b[0], b[1]); w.w = cvt_pk_bf16(b[2], b[3]); return w; }
; __device__ __forceinline__ float rstd_of(const float* ssq, int row) { const f32x4 a = *(const f32x4*)(ssq + (size_t)row * 4);
;     return __builtin_amdgcn_rsqf(((a[0] + a[1]) + (a[2] + a[3])) * (1.0f / 1024.0f) + 1e-6f); }
; __device__ __forceinline__ float sigm(float g) { return __builtin_amdgcn_rcpf(1.0f + __builtin_amdgcn_exp2f(-1.4426950408889634f * g)); }
;     __device__ __forceinline__ void operator()(const f32x4 (&acc)[2][2][4][2], const Unit& u, int wr, int wc, int fr, int fq) const {
;     ...
;             for (int m = 0; m < 4; ++m) { if (m == 0) asm volatile("" ::: "memory"); const int row = row0 + ai * HALF + m * 16; const float rs = rstd_of(ssq, row);
;                 f32x4 o[2];
; #pragma unroll
;                 for (int n = 0; n < 2; ++n) { const f32x4 g = acc[ai][0][m][n] * rs, up = acc[ai][1][m][n] * rs;
; #pragma unroll
;                     for (int e = 0; e < 4; ++e) o[n][e] = g[e] * sigm(g[e]) * up[e]; }
;                 *(u32x4*)(O + (size_t)row * 2816 + col0) = pack8(o[0], o[1]); }
	v_mov_b64_e32 v[98:99], v[158:159]
	v_mov_b64_e32 v[100:101], v[160:161]
	v_mov_b32_e32 v102, v99
	v_mov_b32_e32 v103, v100
	v_mov_b32_e32 v99, v101
	v_pk_add_f32 v[98:99], v[102:103], v[98:99]
	s_nop 0
	v_add_f32_e32 v97, v98, v99
	v_fmamk_f32 v97, v97, 0x3a800000, v231
	v_rsq_f32_e32 v98, v97
	v_mov_b32_e32 v191, v97
	v_mul_f32_e32 v190, 0xbfb8aa3b, v98
	v_mul_f32_e32 v182, v92, v190
	v_mul_f32_e32 v183, v93, v190
	v_mul_f32_e32 v184, v94, v190
	v_mul_f32_e32 v185, v95, v190
	v_mul_f32_e32 v186, v88, v190
	v_mul_f32_e32 v187, v89, v190
	v_mul_f32_e32 v188, v90, v190
	v_mul_f32_e32 v189, v91, v190
	v_exp_f32_e32 v182, v182
	v_exp_f32_e32 v183, v183
	v_exp_f32_e32 v184, v184
	v_exp_f32_e32 v185, v185
	v_exp_f32_e32 v186, v186
	v_exp_f32_e32 v187, v187
	v_exp_f32_e32 v188, v188
	v_exp_f32_e32 v189, v189
	v_fma_f32 v182, v182, v191, v191
	v_fma_f32 v183, v183, v191, v191
	v_fma_f32 v184, v184, v191, v191
	v_fma_f32 v185, v185, v191, v191
	v_fma_f32 v186, v186, v191, v191
	v_fma_f32 v187, v187, v191, v191
	v_fma_f32 v188, v188, v191, v191
	v_fma_f32 v189, v189, v191, v191
	v_rcp_f32_e32 v182, v182
	v_rcp_f32_e32 v183, v183
	v_rcp_f32_e32 v184, v184
	v_rcp_f32_e32 v185, v185
	v_rcp_f32_e32 v186, v186
	v_rcp_f32_e32 v187, v187
	v_rcp_f32_e32 v188, v188
	v_rcp_f32_e32 v189, v189
	v_pk_mul_f32 v[84:85], v[92:93], v[84:85]
	v_pk_mul_f32 v[86:87], v[94:95], v[86:87]
	v_pk_mul_f32 v[88:89], v[88:89], v[80:81]
	v_pk_mul_f32 v[90:91], v[90:91], v[82:83]
	v_pk_mul_f32 v[84:85], v[84:85], v[182:183]
	v_pk_mul_f32 v[86:87], v[86:87], v[184:185]
	v_pk_mul_f32 v[88:89], v[88:89], v[186:187]
	v_pk_mul_f32 v[90:91], v[90:91], v[188:189]
	v_cvt_pk_bf16_f32 v80, v84, v85
	v_mad_i64_i32 v[84:85], s[0:1], v96, s92, v[118:119]
	v_cvt_pk_bf16_f32 v81, v86, v87
	v_cvt_pk_bf16_f32 v82, v88, v89
	v_cvt_pk_bf16_f32 v83, v90, v91
	v_lshl_add_u64 v[84:85], v[84:85], 0, v[120:121]
	global_store_dwordx4 v[84:85], v[80:83], off
	s_nop 1
	v_or_b32_e32 v80, 48, v136
	v_ashrrev_i32_e32 v81, 31, v80
	v_lshl_add_u64 v[82:83], v[80:81], 4, s[18:19]
	s_waitcnt vmcnt(7)
	v_mov_b64_e32 v[82:83], v[162:163]
	v_mov_b64_e32 v[84:85], v[164:165]
	v_mov_b32_e32 v86, v83
	v_mov_b32_e32 v87, v84
	v_mov_b32_e32 v83, v85
	v_pk_add_f32 v[82:83], v[86:87], v[82:83]
	s_nop 0
	v_add_f32_e32 v81, v82, v83
	v_fmamk_f32 v81, v81, 0x3a800000, v231
	v_rsq_f32_e32 v82, v81
	v_mov_b32_e32 v191, v81
	v_mul_f32_e32 v190, 0xbfb8aa3b, v82
	v_mul_f32_e32 v182, v76, v190
	v_mul_f32_e32 v183, v77, v190
	v_mul_f32_e32 v184, v78, v190
	v_mul_f32_e32 v185, v79, v190
	v_mul_f32_e32 v186, v72, v190
	v_mul_f32_e32 v187, v73, v190
	v_mul_f32_e32 v188, v74, v190
	v_mul_f32_e32 v189, v75, v190
	v_exp_f32_e32 v182, v182
	v_exp_f32_e32 v183, v183
	v_exp_f32_e32 v184, v184
	v_exp_f32_e32 v185, v185
	v_exp_f32_e32 v186, v186
	v_exp_f32_e32 v187, v187
	v_exp_f32_e32 v188, v188
	v_exp_f32_e32 v189, v189
	v_fma_f32 v182, v182, v191, v191
	v_fma_f32 v183, v183, v191, v191
	v_fma_f32 v184, v184, v191, v191
	v_fma_f32 v185, v185, v191, v191
	v_fma_f32 v186, v186, v191, v191
	v_fma_f32 v187, v187, v191, v191
	v_fma_f32 v188, v188, v191, v191
	v_fma_f32 v189, v189, v191, v191
	v_rcp_f32_e32 v182, v182
	v_rcp_f32_e32 v183, v183
	v_rcp_f32_e32 v184, v184
	v_rcp_f32_e32 v185, v185
	v_rcp_f32_e32 v186, v186
	v_rcp_f32_e32 v187, v187
	v_rcp_f32_e32 v188, v188
	v_rcp_f32_e32 v189, v189
	v_pk_mul_f32 v[68:69], v[76:77], v[68:69]
	v_pk_mul_f32 v[70:71], v[78:79], v[70:71]
	v_pk_mul_f32 v[72:73], v[72:73], v[64:65]
	v_pk_mul_f32 v[74:75], v[74:75], v[66:67]
	v_pk_mul_f32 v[68:69], v[68:69], v[182:183]
	v_pk_mul_f32 v[70:71], v[70:71], v[184:185]
	v_pk_mul_f32 v[72:73], v[72:73], v[186:187]
	v_pk_mul_f32 v[74:75], v[74:75], v[188:189]
	v_cvt_pk_bf16_f32 v64, v68, v69
	v_mad_i64_i32 v[68:69], s[0:1], v80, s92, v[118:119]
	v_cvt_pk_bf16_f32 v65, v70, v71
	v_cvt_pk_bf16_f32 v66, v72, v73
	v_cvt_pk_bf16_f32 v67, v74, v75
	v_lshl_add_u64 v[68:69], v[68:69], 0, v[120:121]
	global_store_dwordx4 v[68:69], v[64:67], off
	s_nop 1
	v_add_u32_e32 v64, 0x80, v136
	v_ashrrev_i32_e32 v65, 31, v64
	v_lshl_add_u64 v[66:67], v[64:65], 4, s[18:19]
	s_waitcnt vmcnt(7)
	v_mov_b64_e32 v[66:67], v[166:167]
	v_mov_b64_e32 v[68:69], v[168:169]
	v_mov_b32_e32 v70, v67
	v_mov_b32_e32 v71, v68
	v_mov_b32_e32 v67, v69
	v_pk_add_f32 v[66:67], v[70:71], v[66:67]
	s_nop 0
	v_add_f32_e32 v65, v66, v67
	v_fmamk_f32 v65, v65, 0x3a800000, v231
	v_rsq_f32_e32 v66, v65
	v_mov_b32_e32 v191, v65
	v_mul_f32_e32 v190, 0xbfb8aa3b, v66
	v_mul_f32_e32 v182, v60, v190
	v_mul_f32_e32 v183, v61, v190
	v_mul_f32_e32 v184, v62, v190
	v_mul_f32_e32 v185, v63, v190
	v_mul_f32_e32 v186, v56, v190
	v_mul_f32_e32 v187, v57, v190
	v_mul_f32_e32 v188, v58, v190
	v_mul_f32_e32 v189, v59, v190
	v_exp_f32_e32 v182, v182
	v_exp_f32_e32 v183, v183
	v_exp_f32_e32 v184, v184
	v_exp_f32_e32 v185, v185
	v_exp_f32_e32 v186, v186
	v_exp_f32_e32 v187, v187
	v_exp_f32_e32 v188, v188
	v_exp_f32_e32 v189, v189
	v_fma_f32 v182, v182, v191, v191
	v_fma_f32 v183, v183, v191, v191
	v_fma_f32 v184, v184, v191, v191
	v_fma_f32 v185, v185, v191, v191
	v_fma_f32 v186, v186, v191, v191
	v_fma_f32 v187, v187, v191, v191
	v_fma_f32 v188, v188, v191, v191
	v_fma_f32 v189, v189, v191, v191
	v_rcp_f32_e32 v182, v182
	v_rcp_f32_e32 v183, v183
	v_rcp_f32_e32 v184, v184
	v_rcp_f32_e32 v185, v185
	v_rcp_f32_e32 v186, v186
	v_rcp_f32_e32 v187, v187
	v_rcp_f32_e32 v188, v188
	v_rcp_f32_e32 v189, v189
	v_pk_mul_f32 v[52:53], v[60:61], v[52:53]
	v_pk_mul_f32 v[54:55], v[62:63], v[54:55]
	v_pk_mul_f32 v[56:57], v[56:57], v[48:49]
	v_pk_mul_f32 v[58:59], v[58:59], v[50:51]
	v_pk_mul_f32 v[52:53], v[52:53], v[182:183]
	v_pk_mul_f32 v[54:55], v[54:55], v[184:185]
	v_pk_mul_f32 v[56:57], v[56:57], v[186:187]
	v_pk_mul_f32 v[58:59], v[58:59], v[188:189]
	v_cvt_pk_bf16_f32 v48, v52, v53
	v_mad_i64_i32 v[52:53], s[0:1], v64, s92, v[118:119]
	v_cvt_pk_bf16_f32 v49, v54, v55
	v_cvt_pk_bf16_f32 v50, v56, v57
	v_cvt_pk_bf16_f32 v51, v58, v59
	v_lshl_add_u64 v[52:53], v[52:53], 0, v[120:121]
	global_store_dwordx4 v[52:53], v[48:51], off
	s_nop 1
	v_add_u32_e32 v48, 0x90, v136
	v_ashrrev_i32_e32 v49, 31, v48
	v_lshl_add_u64 v[50:51], v[48:49], 4, s[18:19]
	s_waitcnt vmcnt(7)
; __device__ __forceinline__ u32x4 pack8(const f32x4 a, const f32x4 b) { u32x4 w; w.x = cvt_pk_bf16(a[0], a[1]); w.y = cvt_pk_bf16(a[2], a[3]); w.z = cvt_pk_bf16(b[0], b[1]); w.w = cvt_pk_bf16(b[2], b[3]); return w; }
; __device__ __forceinline__ float sigm(float g) { return __builtin_amdgcn_rcpf(1.0f + __builtin_amdgcn_exp2f(-1.4426950408889634f * g)); }
; #define PG8_BAR __builtin_amdgcn_s_barrier()
;     __device__ __forceinline__ void operator()(const f32x4 (&acc)[2][2][4][2], const Unit& u, int wr, int wc, int fr, int fq) const {
;     ...
;             for (int m = 0; m < 4; ++m) { if (m == 0) asm volatile("" ::: "memory"); const int row = row0 + ai * HALF + m * 16; const float rs = rstd_of(ssq, row);
;                 f32x4 o[2];
; #pragma unroll
;                 for (int n = 0; n < 2; ++n) { const f32x4 g = acc[ai][0][m][n] * rs, up = acc[ai][1][m][n] * rs;
; #pragma unroll
;                     for (int e = 0; e < 4; ++e) o[n][e] = g[e] * sigm(g[e]) * up[e]; }
;                 *(u32x4*)(O + (size_t)row * 2816 + col0) = pack8(o[0], o[1]); }
; template <class Epi, class Sched, bool ALIGN_EPI = false, bool SP2 = false>
; __device__ __forceinline__ void gemm_phase(PG8_LAS unsigned char* lds, const Gemm g, const Sched& S, const Epi& E) {
;     ...
;         if constexpr (!Epi::AFTER_DRAIN) { E(acc, cur, wr, wc, fr, fq); S.done(cur); }
;         if (!has_next) break;
; #pragma unroll
;         for (int a = 0; a < 2; ++a)
; #pragma unroll
;             for (int b = 0; b < 2; ++b)
; #pragma unroll
;                 for (int m = 0; m < 4; ++m)
; #pragma unroll
;                     for (int n = 0; n < 2; ++n) acc[a][b][m][n] = (f32x4){0.f, 0.f, 0.f, 0.f};
;         cur = nxt; cA = nA; cB = nB; ++ui;
;         if constexpr (ALIGN_EPI) { if (wr == 1) PG8_BAR; }
	v_mov_b64_e32 v[50:51], v[170:171]
	v_mov_b64_e32 v[52:53], v[172:173]
	v_mov_b32_e32 v54, v51
	v_mov_b32_e32 v55, v52
	v_mov_b32_e32 v51, v53
	v_pk_add_f32 v[50:51], v[54:55], v[50:51]
	s_nop 0
	v_add_f32_e32 v49, v50, v51
	v_fmamk_f32 v49, v49, 0x3a800000, v231
	v_rsq_f32_e32 v50, v49
	v_mov_b32_e32 v191, v49
	v_mul_f32_e32 v190, 0xbfb8aa3b, v50
	v_mul_f32_e32 v182, v44, v190
	v_mul_f32_e32 v183, v45, v190
	v_mul_f32_e32 v184, v46, v190
	v_mul_f32_e32 v185, v47, v190
	v_mul_f32_e32 v186, v40, v190
	v_mul_f32_e32 v187, v41, v190
	v_mul_f32_e32 v188, v42, v190
	v_mul_f32_e32 v189, v43, v190
	v_exp_f32_e32 v182, v182
	v_exp_f32_e32 v183, v183
	v_exp_f32_e32 v184, v184
	v_exp_f32_e32 v185, v185
	v_exp_f32_e32 v186, v186
	v_exp_f32_e32 v187, v187
	v_exp_f32_e32 v188, v188
	v_exp_f32_e32 v189, v189
	v_fma_f32 v182, v182, v191, v191
	v_fma_f32 v183, v183, v191, v191
	v_fma_f32 v184, v184, v191, v191
	v_fma_f32 v185, v185, v191, v191
	v_fma_f32 v186, v186, v191, v191
	v_fma_f32 v187, v187, v191, v191
	v_fma_f32 v188, v188, v191, v191
	v_fma_f32 v189, v189, v191, v191
	v_rcp_f32_e32 v182, v182
	v_rcp_f32_e32 v183, v183
	v_rcp_f32_e32 v184, v184
	v_rcp_f32_e32 v185, v185
	v_rcp_f32_e32 v186, v186
	v_rcp_f32_e32 v187, v187
	v_rcp_f32_e32 v188, v188
	v_rcp_f32_e32 v189, v189
	v_pk_mul_f32 v[36:37], v[44:45], v[36:37]
	v_pk_mul_f32 v[38:39], v[46:47], v[38:39]
	v_pk_mul_f32 v[40:41], v[40:41], v[32:33]
	v_pk_mul_f32 v[42:43], v[42:43], v[34:35]
	v_pk_mul_f32 v[36:37], v[36:37], v[182:183]
	v_pk_mul_f32 v[38:39], v[38:39], v[184:185]
	v_pk_mul_f32 v[40:41], v[40:41], v[186:187]
	v_pk_mul_f32 v[42:43], v[42:43], v[188:189]
	v_cvt_pk_bf16_f32 v32, v36, v37
	v_mad_i64_i32 v[36:37], s[0:1], v48, s92, v[118:119]
	v_cvt_pk_bf16_f32 v33, v38, v39
	v_cvt_pk_bf16_f32 v34, v40, v41
	v_cvt_pk_bf16_f32 v35, v42, v43
	v_lshl_add_u64 v[36:37], v[36:37], 0, v[120:121]
	global_store_dwordx4 v[36:37], v[32:35], off
	s_nop 1
	v_add_u32_e32 v32, 0xa0, v136
	v_ashrrev_i32_e32 v33, 31, v32
	v_lshl_add_u64 v[34:35], v[32:33], 4, s[18:19]
	s_waitcnt vmcnt(7)
	v_mov_b64_e32 v[34:35], v[174:175]
	v_mov_b64_e32 v[36:37], v[176:177]
	v_mov_b32_e32 v38, v35
	v_mov_b32_e32 v39, v36
	v_mov_b32_e32 v35, v37
	v_pk_add_f32 v[34:35], v[38:39], v[34:35]
	s_nop 0
	v_add_f32_e32 v33, v34, v35
	v_fmamk_f32 v33, v33, 0x3a800000, v231
	v_rsq_f32_e32 v34, v33
	v_mov_b32_e32 v191, v33
	v_mul_f32_e32 v190, 0xbfb8aa3b, v34
	v_mul_f32_e32 v182, v28, v190
	v_mul_f32_e32 v183, v29, v190
	v_mul_f32_e32 v184, v30, v190
	v_mul_f32_e32 v185, v31, v190
	v_mul_f32_e32 v186, v24, v190
	v_mul_f32_e32 v187, v25, v190
	v_mul_f32_e32 v188, v26, v190
	v_mul_f32_e32 v189, v27, v190
	v_exp_f32_e32 v182, v182
	v_exp_f32_e32 v183, v183
	v_exp_f32_e32 v184, v184
	v_exp_f32_e32 v185, v185
	v_exp_f32_e32 v186, v186
	v_exp_f32_e32 v187, v187
	v_exp_f32_e32 v188, v188
	v_exp_f32_e32 v189, v189
	v_fma_f32 v182, v182, v191, v191
	v_fma_f32 v183, v183, v191, v191
	v_fma_f32 v184, v184, v191, v191
	v_fma_f32 v185, v185, v191, v191
	v_fma_f32 v186, v186, v191, v191
	v_fma_f32 v187, v187, v191, v191
	v_fma_f32 v188, v188, v191, v191
	v_fma_f32 v189, v189, v191, v191
	v_rcp_f32_e32 v182, v182
	v_rcp_f32_e32 v183, v183
	v_rcp_f32_e32 v184, v184
	v_rcp_f32_e32 v185, v185
	v_rcp_f32_e32 v186, v186
	v_rcp_f32_e32 v187, v187
	v_rcp_f32_e32 v188, v188
	v_rcp_f32_e32 v189, v189
	v_pk_mul_f32 v[20:21], v[28:29], v[20:21]
	v_pk_mul_f32 v[22:23], v[30:31], v[22:23]
	v_pk_mul_f32 v[24:25], v[24:25], v[16:17]
	v_pk_mul_f32 v[26:27], v[26:27], v[18:19]
	v_pk_mul_f32 v[20:21], v[20:21], v[182:183]
	v_pk_mul_f32 v[22:23], v[22:23], v[184:185]
	v_pk_mul_f32 v[24:25], v[24:25], v[186:187]
	v_pk_mul_f32 v[26:27], v[26:27], v[188:189]
	v_cvt_pk_bf16_f32 v16, v20, v21
	v_mad_i64_i32 v[20:21], s[0:1], v32, s92, v[118:119]
	v_cvt_pk_bf16_f32 v17, v22, v23
	v_cvt_pk_bf16_f32 v18, v24, v25
	v_cvt_pk_bf16_f32 v19, v26, v27
	v_lshl_add_u64 v[20:21], v[20:21], 0, v[120:121]
	global_store_dwordx4 v[20:21], v[16:19], off
	s_nop 1
	v_add_u32_e32 v16, 0xb0, v136
	v_ashrrev_i32_e32 v17, 31, v16
	v_lshl_add_u64 v[18:19], v[16:17], 4, s[18:19]
	s_waitcnt vmcnt(7)
	v_mov_b64_e32 v[18:19], v[178:179]
	v_mov_b64_e32 v[20:21], v[180:181]
	v_mov_b32_e32 v22, v19
	v_mov_b32_e32 v23, v20
	v_mov_b32_e32 v19, v21
	v_pk_add_f32 v[18:19], v[22:23], v[18:19]
	s_nop 0
	v_add_f32_e32 v17, v18, v19
	v_fmamk_f32 v17, v17, 0x3a800000, v231
	v_rsq_f32_e32 v18, v17
	v_mov_b32_e32 v191, v17
	v_mul_f32_e32 v190, 0xbfb8aa3b, v18
	v_mul_f32_e32 v182, v12, v190
	v_mul_f32_e32 v183, v13, v190
	v_mul_f32_e32 v184, v14, v190
	v_mul_f32_e32 v185, v15, v190
	v_mul_f32_e32 v186, v8, v190
	v_mul_f32_e32 v187, v9, v190
	v_mul_f32_e32 v188, v10, v190
	v_mul_f32_e32 v189, v11, v190
	v_exp_f32_e32 v182, v182
	v_exp_f32_e32 v183, v183
	v_exp_f32_e32 v184, v184
	v_exp_f32_e32 v185, v185
	v_exp_f32_e32 v186, v186
	v_exp_f32_e32 v187, v187
	v_exp_f32_e32 v188, v188
	v_exp_f32_e32 v189, v189
	v_fma_f32 v182, v182, v191, v191
	v_fma_f32 v183, v183, v191, v191
	v_fma_f32 v184, v184, v191, v191
	v_fma_f32 v185, v185, v191, v191
	v_fma_f32 v186, v186, v191, v191
	v_fma_f32 v187, v187, v191, v191
	v_fma_f32 v188, v188, v191, v191
	v_fma_f32 v189, v189, v191, v191
	v_rcp_f32_e32 v182, v182
	v_rcp_f32_e32 v183, v183
	v_rcp_f32_e32 v184, v184
	v_rcp_f32_e32 v185, v185
	v_rcp_f32_e32 v186, v186
	v_rcp_f32_e32 v187, v187
	v_rcp_f32_e32 v188, v188
	v_rcp_f32_e32 v189, v189
	v_pk_mul_f32 v[4:5], v[12:13], v[4:5]
	v_pk_mul_f32 v[6:7], v[14:15], v[6:7]
	v_pk_mul_f32 v[8:9], v[8:9], v[0:1]
	v_pk_mul_f32 v[10:11], v[10:11], v[2:3]
	v_pk_mul_f32 v[4:5], v[4:5], v[182:183]
	v_pk_mul_f32 v[6:7], v[6:7], v[184:185]
	v_pk_mul_f32 v[8:9], v[8:9], v[186:187]
	v_pk_mul_f32 v[10:11], v[10:11], v[188:189]
	v_cvt_pk_bf16_f32 v0, v4, v5
	v_mad_i64_i32 v[4:5], s[0:1], v16, s92, v[118:119]
	v_cvt_pk_bf16_f32 v1, v6, v7
	v_cvt_pk_bf16_f32 v2, v8, v9
	v_cvt_pk_bf16_f32 v3, v10, v11
	v_lshl_add_u64 v[4:5], v[4:5], 0, v[120:121]
	s_mov_b64 s[0:1], -1
	global_store_dwordx4 v[4:5], v[0:3], off
	s_cbranch_vccnz .LBB0_114
	s_andn2_b64 vcc, exec, s[10:11]
	s_cbranch_vccnz .LBB0_113
	s_barrier
	s_branch .LBB0_113
